# stack + NSA flush read-modify-write loads issued together (8 in flight) for the selected and window flushes
# baseline (speedup 1.0000x reference)
; DI float bflo(unsigned u) { return __uint_as_float(u << 16); }
; DI float bfhi(unsigned u) { return __uint_as_float(u & 0xffff0000u); }
; template <bool FIRST>
; DI void nsa_flush(const int quad, bf16_t* optr, const AttnSt& st, const float (&sc)[2]) {
; #pragma unroll
;   for (int h = 0; h < 2; ++h)
; #pragma unroll
;     for (int dt = 0; dt < 4; ++dt) {
;       uint2* q = (uint2*)(optr + h * 64 + dt * 16 + quad * 4);
;       f32x4 o = st.O[h][dt] * sc[h];
;       if (!FIRST) {
;         uint2 pv = *q;
;         o[0] += bflo(pv.x); o[1] += bfhi(pv.x); o[2] += bflo(pv.y); o[3] += bfhi(pv.y);
;       }
;       uint2 u;
;       u.x = pack2(o[0], o[1]);
;       u.y = pack2(o[2], o[3]);
;       *q = u;
;     }
; }
.LBB0_664:
	s_or_b64 exec, exec, s[2:3]
	global_load_dwordx2 v[220:221], v[158:159], off
	global_load_dwordx2 v[222:223], v[158:159], off offset:32
	global_load_dwordx2 v[224:225], v[158:159], off offset:64
	global_load_dwordx2 v[226:227], v[158:159], off offset:96
	global_load_dwordx2 v[228:229], v[158:159], off offset:128
	global_load_dwordx2 v[230:231], v[158:159], off offset:160
	global_load_dwordx2 v[232:233], v[158:159], off offset:192
	global_load_dwordx2 v[234:235], v[158:159], off offset:224
	v_mov_b32_e32 v3, v2
	s_mov_b32 s6, 1
	s_mov_b64 s[2:3], 0
	s_and_b64 vcc, exec, s[36:37]
	s_waitcnt vmcnt(7)
	v_lshlrev_b32_e32 v10, 16, v220
	v_and_b32_e32 v11, 0xffff0000, v220
	v_lshlrev_b32_e32 v8, 16, v221
	v_and_b32_e32 v9, 0xffff0000, v221
	v_pk_fma_f32 v[10:11], v[46:47], v[4:5], v[10:11]
	v_pk_fma_f32 v[8:9], v[48:49], v[6:7], v[8:9]
	v_cvt_pk_bf16_f32 v10, v10, v11
	v_cvt_pk_bf16_f32 v11, v8, v9

; DI float bflo(unsigned u) { return __uint_as_float(u << 16); }
; DI float bfhi(unsigned u) { return __uint_as_float(u & 0xffff0000u); }
; template <bool FIRST>
; DI void nsa_flush(const int quad, bf16_t* optr, const AttnSt& st, const float (&sc)[2]) {
; #pragma unroll
;   for (int h = 0; h < 2; ++h)
; #pragma unroll
;     for (int dt = 0; dt < 4; ++dt) {
;       uint2* q = (uint2*)(optr + h * 64 + dt * 16 + quad * 4);
;       f32x4 o = st.O[h][dt] * sc[h];
;       if (!FIRST) {
;         uint2 pv = *q;
;         o[0] += bflo(pv.x); o[1] += bfhi(pv.x); o[2] += bflo(pv.y); o[3] += bfhi(pv.y);
;       }
;       uint2 u;
;       u.x = pack2(o[0], o[1]);
;       u.y = pack2(o[2], o[3]);
;       *q = u;
;     }
; }
	s_nop 0
	global_store_dwordx2 v[158:159], v[10:11], off
	s_waitcnt vmcnt(7)
	v_lshlrev_b32_e32 v10, 16, v222
	v_and_b32_e32 v11, 0xffff0000, v222
	v_lshlrev_b32_e32 v8, 16, v223
	v_and_b32_e32 v9, 0xffff0000, v223
	v_pk_fma_f32 v[10:11], v[42:43], v[4:5], v[10:11]
	v_pk_fma_f32 v[8:9], v[44:45], v[6:7], v[8:9]
	v_cvt_pk_bf16_f32 v10, v10, v11
	v_cvt_pk_bf16_f32 v11, v8, v9

; DI float bflo(unsigned u) { return __uint_as_float(u << 16); }
; DI float bfhi(unsigned u) { return __uint_as_float(u & 0xffff0000u); }
; template <bool FIRST>
; DI void nsa_flush(const int quad, bf16_t* optr, const AttnSt& st, const float (&sc)[2]) {
; #pragma unroll
;   for (int h = 0; h < 2; ++h)
; #pragma unroll
;     for (int dt = 0; dt < 4; ++dt) {
;       uint2* q = (uint2*)(optr + h * 64 + dt * 16 + quad * 4);
;       f32x4 o = st.O[h][dt] * sc[h];
;       if (!FIRST) {
;         uint2 pv = *q;
;         o[0] += bflo(pv.x); o[1] += bfhi(pv.x); o[2] += bflo(pv.y); o[3] += bfhi(pv.y);
;       }
;       uint2 u;
;       u.x = pack2(o[0], o[1]);
;       u.y = pack2(o[2], o[3]);
;       *q = u;
;     }
; }
	s_nop 0
	global_store_dwordx2 v[158:159], v[10:11], off offset:32
	s_waitcnt vmcnt(7)
	v_lshlrev_b32_e32 v10, 16, v224
	v_and_b32_e32 v11, 0xffff0000, v224
	v_lshlrev_b32_e32 v8, 16, v225
	v_and_b32_e32 v9, 0xffff0000, v225
	v_pk_fma_f32 v[10:11], v[38:39], v[4:5], v[10:11]
	v_pk_fma_f32 v[8:9], v[40:41], v[6:7], v[8:9]
	v_cvt_pk_bf16_f32 v10, v10, v11
	v_cvt_pk_bf16_f32 v11, v8, v9

; DI float bflo(unsigned u) { return __uint_as_float(u << 16); }
; DI float bfhi(unsigned u) { return __uint_as_float(u & 0xffff0000u); }
; template <bool FIRST>
; DI void nsa_flush(const int quad, bf16_t* optr, const AttnSt& st, const float (&sc)[2]) {
; #pragma unroll
;   for (int h = 0; h < 2; ++h)
; #pragma unroll
;     for (int dt = 0; dt < 4; ++dt) {
;       uint2* q = (uint2*)(optr + h * 64 + dt * 16 + quad * 4);
;       f32x4 o = st.O[h][dt] * sc[h];
;       if (!FIRST) {
;         uint2 pv = *q;
;         o[0] += bflo(pv.x); o[1] += bfhi(pv.x); o[2] += bflo(pv.y); o[3] += bfhi(pv.y);
;       }
;       uint2 u;
;       u.x = pack2(o[0], o[1]);
;       u.y = pack2(o[2], o[3]);
;       *q = u;
;     }
; }
	s_nop 0
	global_store_dwordx2 v[158:159], v[10:11], off offset:64
	s_waitcnt vmcnt(7)
	v_lshlrev_b32_e32 v10, 16, v226
	v_and_b32_e32 v11, 0xffff0000, v226
	v_lshlrev_b32_e32 v8, 16, v227
	v_and_b32_e32 v9, 0xffff0000, v227
	v_pk_fma_f32 v[4:5], v[34:35], v[4:5], v[10:11]
	v_pk_fma_f32 v[6:7], v[36:37], v[6:7], v[8:9]
	v_cvt_pk_bf16_f32 v4, v4, v5
	v_cvt_pk_bf16_f32 v5, v6, v7

; DI float bflo(unsigned u) { return __uint_as_float(u << 16); }
; DI float bfhi(unsigned u) { return __uint_as_float(u & 0xffff0000u); }
; template <bool FIRST>
; DI void nsa_flush(const int quad, bf16_t* optr, const AttnSt& st, const float (&sc)[2]) {
; #pragma unroll
;   for (int h = 0; h < 2; ++h)
; #pragma unroll
;     for (int dt = 0; dt < 4; ++dt) {
;       uint2* q = (uint2*)(optr + h * 64 + dt * 16 + quad * 4);
;       f32x4 o = st.O[h][dt] * sc[h];
;       if (!FIRST) {
;         uint2 pv = *q;
;         o[0] += bflo(pv.x); o[1] += bfhi(pv.x); o[2] += bflo(pv.y); o[3] += bfhi(pv.y);
;       }
;       uint2 u;
;       u.x = pack2(o[0], o[1]);
;       u.y = pack2(o[2], o[3]);
;       *q = u;
;     }
; }
	s_waitcnt vmcnt(6)
	v_lshlrev_b32_e32 v8, 16, v228
	global_store_dwordx2 v[158:159], v[4:5], off offset:96
	v_mov_b32_e32 v4, v2
	v_mov_b32_e32 v5, v2
	v_and_b32_e32 v9, 0xffff0000, v228
	v_lshlrev_b32_e32 v6, 16, v229
	v_and_b32_e32 v7, 0xffff0000, v229
	v_pk_fma_f32 v[8:9], v[30:31], v[4:5], v[8:9]
	v_pk_fma_f32 v[6:7], v[32:33], v[2:3], v[6:7]
	v_cvt_pk_bf16_f32 v8, v8, v9
	v_cvt_pk_bf16_f32 v9, v6, v7

; DI float bflo(unsigned u) { return __uint_as_float(u << 16); }
; DI float bfhi(unsigned u) { return __uint_as_float(u & 0xffff0000u); }
; template <bool FIRST>
; DI void nsa_flush(const int quad, bf16_t* optr, const AttnSt& st, const float (&sc)[2]) {
; #pragma unroll
;   for (int h = 0; h < 2; ++h)
; #pragma unroll
;     for (int dt = 0; dt < 4; ++dt) {
;       uint2* q = (uint2*)(optr + h * 64 + dt * 16 + quad * 4);
;       f32x4 o = st.O[h][dt] * sc[h];
;       if (!FIRST) {
;         uint2 pv = *q;
;         o[0] += bflo(pv.x); o[1] += bfhi(pv.x); o[2] += bflo(pv.y); o[3] += bfhi(pv.y);
;       }
;       uint2 u;
;       u.x = pack2(o[0], o[1]);
;       u.y = pack2(o[2], o[3]);
;       *q = u;
;     }
; }
	s_nop 0
	global_store_dwordx2 v[158:159], v[8:9], off offset:128
	s_waitcnt vmcnt(7)
	v_lshlrev_b32_e32 v8, 16, v230
	v_and_b32_e32 v9, 0xffff0000, v230
	v_lshlrev_b32_e32 v6, 16, v231
	v_and_b32_e32 v7, 0xffff0000, v231
	v_pk_fma_f32 v[8:9], v[26:27], v[4:5], v[8:9]
	v_pk_fma_f32 v[6:7], v[28:29], v[2:3], v[6:7]
	v_cvt_pk_bf16_f32 v8, v8, v9
	v_cvt_pk_bf16_f32 v9, v6, v7

; DI float bflo(unsigned u) { return __uint_as_float(u << 16); }
; DI float bfhi(unsigned u) { return __uint_as_float(u & 0xffff0000u); }
; template <bool FIRST>
; DI void nsa_flush(const int quad, bf16_t* optr, const AttnSt& st, const float (&sc)[2]) {
; #pragma unroll
;   for (int h = 0; h < 2; ++h)
; #pragma unroll
;     for (int dt = 0; dt < 4; ++dt) {
;       uint2* q = (uint2*)(optr + h * 64 + dt * 16 + quad * 4);
;       f32x4 o = st.O[h][dt] * sc[h];
;       if (!FIRST) {
;         uint2 pv = *q;
;         o[0] += bflo(pv.x); o[1] += bfhi(pv.x); o[2] += bflo(pv.y); o[3] += bfhi(pv.y);
;       }
;       uint2 u;
;       u.x = pack2(o[0], o[1]);
;       u.y = pack2(o[2], o[3]);
;       *q = u;
;     }
; }
	s_nop 0
	global_store_dwordx2 v[158:159], v[8:9], off offset:160
	s_waitcnt vmcnt(7)
	v_lshlrev_b32_e32 v8, 16, v232
	v_and_b32_e32 v9, 0xffff0000, v232
	v_lshlrev_b32_e32 v6, 16, v233
	v_and_b32_e32 v7, 0xffff0000, v233
	v_pk_fma_f32 v[8:9], v[22:23], v[4:5], v[8:9]
	v_pk_fma_f32 v[6:7], v[24:25], v[2:3], v[6:7]
	v_cvt_pk_bf16_f32 v8, v8, v9
	v_cvt_pk_bf16_f32 v9, v6, v7

; DI float bflo(unsigned u) { return __uint_as_float(u << 16); }
; DI float bfhi(unsigned u) { return __uint_as_float(u & 0xffff0000u); }
; template <bool FIRST>
; DI void nsa_flush(const int quad, bf16_t* optr, const AttnSt& st, const float (&sc)[2]) {
; #pragma unroll
;   for (int h = 0; h < 2; ++h)
; #pragma unroll
;     for (int dt = 0; dt < 4; ++dt) {
;       uint2* q = (uint2*)(optr + h * 64 + dt * 16 + quad * 4);
;       f32x4 o = st.O[h][dt] * sc[h];
;       if (!FIRST) {
;         uint2 pv = *q;
;         o[0] += bflo(pv.x); o[1] += bfhi(pv.x); o[2] += bflo(pv.y); o[3] += bfhi(pv.y);
;       }
;       uint2 u;
;       u.x = pack2(o[0], o[1]);
;       u.y = pack2(o[2], o[3]);
;       *q = u;
;     }
; }
	s_nop 0
	global_store_dwordx2 v[158:159], v[8:9], off offset:192
	s_waitcnt vmcnt(7)
	v_lshlrev_b32_e32 v8, 16, v234
	v_and_b32_e32 v9, 0xffff0000, v234
	v_lshlrev_b32_e32 v6, 16, v235
	v_and_b32_e32 v7, 0xffff0000, v235
	v_pk_fma_f32 v[4:5], v[18:19], v[4:5], v[8:9]
	v_pk_fma_f32 v[2:3], v[20:21], v[2:3], v[6:7]
	v_cvt_pk_bf16_f32 v4, v4, v5
	v_cvt_pk_bf16_f32 v5, v2, v3
	global_store_dwordx2 v[158:159], v[4:5], off offset:224
	s_cbranch_vccnz .LBB0_358

; DI float bflo(unsigned u) { return __uint_as_float(u << 16); }
; DI float bfhi(unsigned u) { return __uint_as_float(u & 0xffff0000u); }
; template <bool FIRST>
; DI void nsa_flush(const int quad, bf16_t* optr, const AttnSt& st, const float (&sc)[2]) {
; #pragma unroll
;   for (int h = 0; h < 2; ++h)
; #pragma unroll
;     for (int dt = 0; dt < 4; ++dt) {
;       uint2* q = (uint2*)(optr + h * 64 + dt * 16 + quad * 4);
;       f32x4 o = st.O[h][dt] * sc[h];
;       if (!FIRST) {
;         uint2 pv = *q;
;         o[0] += bflo(pv.x); o[1] += bfhi(pv.x); o[2] += bflo(pv.y); o[3] += bfhi(pv.y);
;       }
;       uint2 u;
;       u.x = pack2(o[0], o[1]);
;       u.y = pack2(o[2], o[3]);
;       *q = u;
;     }
; }
.LBB0_679:
	s_or_b64 exec, exec, s[2:3]
	s_lshl_b32 s28, s7, 1
	v_lshl_add_u64 v[158:159], v[128:129], 0, s[28:29]
	global_load_dwordx2 v[220:221], v[158:159], off
	global_load_dwordx2 v[222:223], v[158:159], off offset:32
	global_load_dwordx2 v[224:225], v[158:159], off offset:64
	global_load_dwordx2 v[226:227], v[158:159], off offset:96
	global_load_dwordx2 v[228:229], v[158:159], off offset:128
	global_load_dwordx2 v[230:231], v[158:159], off offset:160
	global_load_dwordx2 v[232:233], v[158:159], off offset:192
	global_load_dwordx2 v[234:235], v[158:159], off offset:224
	v_mov_b32_e32 v49, v48
	v_mov_b32_e32 v178, v186
	s_mov_b32 s71, s26
	s_mov_b32 s28, s27
	s_waitcnt vmcnt(7)
	v_lshlrev_b32_e32 v54, 16, v220
	v_and_b32_e32 v55, 0xffff0000, v220
	v_lshlrev_b32_e32 v46, 16, v221
	v_and_b32_e32 v47, 0xffff0000, v221
	v_pk_fma_f32 v[50:51], v[50:51], v[56:57], v[54:55]
	v_pk_fma_f32 v[46:47], v[52:53], v[58:59], v[46:47]
	v_cvt_pk_bf16_f32 v50, v50, v51
	v_cvt_pk_bf16_f32 v51, v46, v47

; DI float bflo(unsigned u) { return __uint_as_float(u << 16); }
; DI float bfhi(unsigned u) { return __uint_as_float(u & 0xffff0000u); }
; template <bool FIRST>
; DI void nsa_flush(const int quad, bf16_t* optr, const AttnSt& st, const float (&sc)[2]) {
; #pragma unroll
;   for (int h = 0; h < 2; ++h)
; #pragma unroll
;     for (int dt = 0; dt < 4; ++dt) {
;       uint2* q = (uint2*)(optr + h * 64 + dt * 16 + quad * 4);
;       f32x4 o = st.O[h][dt] * sc[h];
;       if (!FIRST) {
;         uint2 pv = *q;
;         o[0] += bflo(pv.x); o[1] += bfhi(pv.x); o[2] += bflo(pv.y); o[3] += bfhi(pv.y);
;       }
;       uint2 u;
;       u.x = pack2(o[0], o[1]);
;       u.y = pack2(o[2], o[3]);
;       *q = u;
;     }
; }
	s_nop 0
	global_store_dwordx2 v[158:159], v[50:51], off
	s_waitcnt vmcnt(7)
	v_lshlrev_b32_e32 v50, 16, v222
	v_and_b32_e32 v51, 0xffff0000, v222
	v_lshlrev_b32_e32 v46, 16, v223
	v_and_b32_e32 v47, 0xffff0000, v223
	v_pk_fma_f32 v[42:43], v[42:43], v[56:57], v[50:51]
	v_pk_fma_f32 v[44:45], v[44:45], v[58:59], v[46:47]
	v_cvt_pk_bf16_f32 v42, v42, v43
	v_cvt_pk_bf16_f32 v43, v44, v45
	global_store_dwordx2 v[158:159], v[42:43], off offset:32

; DI float bflo(unsigned u) { return __uint_as_float(u << 16); }
; DI float bfhi(unsigned u) { return __uint_as_float(u & 0xffff0000u); }
; template <bool FIRST>
; DI void nsa_flush(const int quad, bf16_t* optr, const AttnSt& st, const float (&sc)[2]) {
; #pragma unroll
;   for (int h = 0; h < 2; ++h)
; #pragma unroll
;     for (int dt = 0; dt < 4; ++dt) {
;       uint2* q = (uint2*)(optr + h * 64 + dt * 16 + quad * 4);
;       f32x4 o = st.O[h][dt] * sc[h];
;       if (!FIRST) {
;         uint2 pv = *q;
;         o[0] += bflo(pv.x); o[1] += bfhi(pv.x); o[2] += bflo(pv.y); o[3] += bfhi(pv.y);
;       }
;       uint2 u;
;       u.x = pack2(o[0], o[1]);
;       u.y = pack2(o[2], o[3]);
;       *q = u;
;     }
; }
	v_mov_b32_e32 v46, 0
	v_mov_b32_e32 v47, v46
	v_mov_b32_e32 v54, v46
	v_mov_b32_e32 v55, v46
	v_mov_b32_e32 v50, v46
	v_mov_b32_e32 v51, v46
	v_mov_b32_e32 v52, v46
	v_mov_b32_e32 v53, v46
	s_waitcnt vmcnt(7)
	v_lshlrev_b32_e32 v44, 16, v224
	v_and_b32_e32 v45, 0xffff0000, v224
	v_lshlrev_b32_e32 v42, 16, v225
	v_and_b32_e32 v43, 0xffff0000, v225
	v_pk_fma_f32 v[38:39], v[38:39], v[56:57], v[44:45]
	v_pk_fma_f32 v[40:41], v[40:41], v[58:59], v[42:43]
	v_cvt_pk_bf16_f32 v38, v38, v39
	v_cvt_pk_bf16_f32 v39, v40, v41
	global_store_dwordx2 v[158:159], v[38:39], off offset:64

; DI float bflo(unsigned u) { return __uint_as_float(u << 16); }
; DI float bfhi(unsigned u) { return __uint_as_float(u & 0xffff0000u); }
; template <bool FIRST>
; DI void nsa_flush(const int quad, bf16_t* optr, const AttnSt& st, const float (&sc)[2]) {
; #pragma unroll
;   for (int h = 0; h < 2; ++h)
; #pragma unroll
;     for (int dt = 0; dt < 4; ++dt) {
;       uint2* q = (uint2*)(optr + h * 64 + dt * 16 + quad * 4);
;       f32x4 o = st.O[h][dt] * sc[h];
;       if (!FIRST) {
;         uint2 pv = *q;
;         o[0] += bflo(pv.x); o[1] += bfhi(pv.x); o[2] += bflo(pv.y); o[3] += bfhi(pv.y);
;       }
;       uint2 u;
;       u.x = pack2(o[0], o[1]);
;       u.y = pack2(o[2], o[3]);
;       *q = u;
;     }
; }
	v_mov_b32_e32 v42, v46
	v_mov_b32_e32 v43, v46
	v_mov_b32_e32 v44, v46
	v_mov_b32_e32 v45, v46
	s_waitcnt vmcnt(7)
	v_lshlrev_b32_e32 v40, 16, v226
	v_and_b32_e32 v41, 0xffff0000, v226
	v_lshlrev_b32_e32 v38, 16, v227
	v_and_b32_e32 v39, 0xffff0000, v227
	v_pk_fma_f32 v[34:35], v[34:35], v[56:57], v[40:41]
	v_pk_fma_f32 v[36:37], v[36:37], v[58:59], v[38:39]
	v_cvt_pk_bf16_f32 v34, v34, v35
	v_cvt_pk_bf16_f32 v35, v36, v37

; DI float bflo(unsigned u) { return __uint_as_float(u << 16); }
; DI float bfhi(unsigned u) { return __uint_as_float(u & 0xffff0000u); }
; template <bool FIRST>
; DI void nsa_flush(const int quad, bf16_t* optr, const AttnSt& st, const float (&sc)[2]) {
; #pragma unroll
;   for (int h = 0; h < 2; ++h)
; #pragma unroll
;     for (int dt = 0; dt < 4; ++dt) {
;       uint2* q = (uint2*)(optr + h * 64 + dt * 16 + quad * 4);
;       f32x4 o = st.O[h][dt] * sc[h];
;       if (!FIRST) {
;         uint2 pv = *q;
;         o[0] += bflo(pv.x); o[1] += bfhi(pv.x); o[2] += bflo(pv.y); o[3] += bfhi(pv.y);
;       }
;       uint2 u;
;       u.x = pack2(o[0], o[1]);
;       u.y = pack2(o[2], o[3]);
;       *q = u;
;     }
; }
	v_mov_b32_e32 v40, v46
	global_store_dwordx2 v[158:159], v[34:35], off offset:96
	v_mov_b32_e32 v34, v48
	v_mov_b32_e32 v35, v48
	v_mov_b32_e32 v41, v46
	v_mov_b32_e32 v56, v46
	v_mov_b32_e32 v57, v46
	s_waitcnt vmcnt(7)
	v_lshlrev_b32_e32 v38, 16, v228
	v_and_b32_e32 v39, 0xffff0000, v228
	v_lshlrev_b32_e32 v36, 16, v229
	v_and_b32_e32 v37, 0xffff0000, v229
	v_pk_fma_f32 v[30:31], v[30:31], v[34:35], v[38:39]
	v_pk_fma_f32 v[32:33], v[32:33], v[48:49], v[36:37]
	v_cvt_pk_bf16_f32 v30, v30, v31
	v_cvt_pk_bf16_f32 v31, v32, v33
	global_store_dwordx2 v[158:159], v[30:31], off offset:128

; DI float bflo(unsigned u) { return __uint_as_float(u << 16); }
; DI float bfhi(unsigned u) { return __uint_as_float(u & 0xffff0000u); }
; template <bool FIRST>
; DI void nsa_flush(const int quad, bf16_t* optr, const AttnSt& st, const float (&sc)[2]) {
; #pragma unroll
;   for (int h = 0; h < 2; ++h)
; #pragma unroll
;     for (int dt = 0; dt < 4; ++dt) {
;       uint2* q = (uint2*)(optr + h * 64 + dt * 16 + quad * 4);
;       f32x4 o = st.O[h][dt] * sc[h];
;       if (!FIRST) {
;         uint2 pv = *q;
;         o[0] += bflo(pv.x); o[1] += bfhi(pv.x); o[2] += bflo(pv.y); o[3] += bfhi(pv.y);
;       }
;       uint2 u;
;       u.x = pack2(o[0], o[1]);
;       u.y = pack2(o[2], o[3]);
;       *q = u;
;     }
; }
	v_mov_b32_e32 v38, v46
	v_mov_b32_e32 v39, v46
	v_mov_b32_e32 v36, v46
	v_mov_b32_e32 v37, v46
	s_waitcnt vmcnt(7)
	v_lshlrev_b32_e32 v32, 16, v230
	v_and_b32_e32 v33, 0xffff0000, v230
	v_lshlrev_b32_e32 v30, 16, v231
	v_and_b32_e32 v31, 0xffff0000, v231
	v_pk_fma_f32 v[26:27], v[26:27], v[34:35], v[32:33]
	v_pk_fma_f32 v[28:29], v[28:29], v[48:49], v[30:31]
	v_cvt_pk_bf16_f32 v26, v26, v27
	v_cvt_pk_bf16_f32 v27, v28, v29
	global_store_dwordx2 v[158:159], v[26:27], off offset:160

; DI float bflo(unsigned u) { return __uint_as_float(u << 16); }
; DI float bfhi(unsigned u) { return __uint_as_float(u & 0xffff0000u); }
; template <bool FIRST>
; DI void nsa_flush(const int quad, bf16_t* optr, const AttnSt& st, const float (&sc)[2]) {
; #pragma unroll
;   for (int h = 0; h < 2; ++h)
; #pragma unroll
;     for (int dt = 0; dt < 4; ++dt) {
;       uint2* q = (uint2*)(optr + h * 64 + dt * 16 + quad * 4);
;       f32x4 o = st.O[h][dt] * sc[h];
;       if (!FIRST) {
;         uint2 pv = *q;
;         o[0] += bflo(pv.x); o[1] += bfhi(pv.x); o[2] += bflo(pv.y); o[3] += bfhi(pv.y);
;       }
;       uint2 u;
;       u.x = pack2(o[0], o[1]);
;       u.y = pack2(o[2], o[3]);
;       *q = u;
;     }
; }
	v_mov_b32_e32 v30, v46
	v_mov_b32_e32 v31, v46
	v_mov_b32_e32 v32, v46
	v_mov_b32_e32 v33, v46
	s_waitcnt vmcnt(7)
	v_lshlrev_b32_e32 v28, 16, v232
	v_and_b32_e32 v29, 0xffff0000, v232
	v_lshlrev_b32_e32 v26, 16, v233
	v_and_b32_e32 v27, 0xffff0000, v233
	v_pk_fma_f32 v[22:23], v[22:23], v[34:35], v[28:29]
	v_pk_fma_f32 v[24:25], v[24:25], v[48:49], v[26:27]
	v_cvt_pk_bf16_f32 v22, v22, v23
	v_cvt_pk_bf16_f32 v23, v24, v25
	global_store_dwordx2 v[158:159], v[22:23], off offset:192

; DI float bflo(unsigned u) { return __uint_as_float(u << 16); }
; DI float bfhi(unsigned u) { return __uint_as_float(u & 0xffff0000u); }
; template <bool FIRST>
; DI void nsa_flush(const int quad, bf16_t* optr, const AttnSt& st, const float (&sc)[2]) {
; #pragma unroll
;   for (int h = 0; h < 2; ++h)
; #pragma unroll
;     for (int dt = 0; dt < 4; ++dt) {
;       uint2* q = (uint2*)(optr + h * 64 + dt * 16 + quad * 4);
;       f32x4 o = st.O[h][dt] * sc[h];
;       if (!FIRST) {
;         uint2 pv = *q;
;         o[0] += bflo(pv.x); o[1] += bfhi(pv.x); o[2] += bflo(pv.y); o[3] += bfhi(pv.y);
;       }
;       uint2 u;
;       u.x = pack2(o[0], o[1]);
;       u.y = pack2(o[2], o[3]);
;       *q = u;
;     }
; }
; template <bool FX>
; DI void nsa_tile(const Params& p, int b, int g, int tile, bf16_t* lds, const float CL) {
;     ...
;     st_reset(st);
;     {
;       const bf16_t* kb = zb + C_KW + g * 64;
;       const int s0 = (cur >= 8) ? cur - 8 : 0;
;       tile64_gload(tid, rk0, rk1, kb + (size_t)s0 * 64 * ZS, ZS);
;       tile64_gload(tid, rv0, rv1, vwT + s0 * 64, TS);
	v_mov_b32_e32 v26, v46
	v_mov_b32_e32 v27, v46
	v_mov_b32_e32 v28, v46
	v_mov_b32_e32 v29, v46
	s_waitcnt vmcnt(7)
	v_lshlrev_b32_e32 v24, 16, v234
	v_and_b32_e32 v25, 0xffff0000, v234
	v_lshlrev_b32_e32 v22, 16, v235
	v_and_b32_e32 v23, 0xffff0000, v235
	v_pk_fma_f32 v[18:19], v[18:19], v[34:35], v[24:25]
	v_pk_fma_f32 v[20:21], v[20:21], v[48:49], v[22:23]
	v_cvt_pk_bf16_f32 v18, v18, v19
	v_cvt_pk_bf16_f32 v19, v20, v21
	global_store_dwordx2 v[158:159], v[18:19], off offset:224
	global_load_dwordx4 v[58:61], v[146:147], off offset:2048
	global_load_dwordx4 v[62:65], v[148:149], off offset:2048
	global_load_dwordx4 v[66:69], v[150:151], off
	global_load_dwordx4 v[70:73], v[152:153], off
	v_mov_b32_e32 v48, v46
	v_mov_b32_e32 v49, v46
	v_mov_b32_e32 v34, v46
	v_mov_b32_e32 v35, v46
	v_mov_b32_e32 v22, v46
	v_mov_b32_e32 v23, v46
	v_mov_b32_e32 v24, v46
	v_mov_b32_e32 v25, v46
	v_mov_b32_e32 v18, v46
	v_mov_b32_e32 v19, v46
	v_mov_b32_e32 v20, v46
	v_mov_b32_e32 v21, v46
	s_branch .LBB0_681
